# latent-norm (q) row loop: gains loaded once before the loop, next row loaded while the current row is reduced
# speedup vs baseline: 1.0000x; 1.0000x over previous
; template <int N>
; __device__ __forceinline__ void lat_norm(const Frame& F, const bf16* src, const float* w, bf16* dst, int nvalid, int ntotal) {
;     constexpr int PER = N / 64;
;     const int gw = F.vcu * NWAVES + F.wave, NGW = F.G * NWAVES;
;     for (int r = gw; r < ntotal; r += NGW) {
;         unsigned xw[PER / 2]; float x[PER]; float s = 0.f;
;         if (r < nvalid) {
; #pragma unroll
;             for (int j = 0; j < PER / 8; ++j) { const v4u t = *((const v4u*)(src + (size_t)r * N + F.lane * PER) + j); xw[4 * j] = t.x; xw[4 * j + 1] = t.y; xw[4 * j + 2] = t.z; xw[4 * j + 3] = t.w; }
.LBB0_631:
	s_cmp_lt_i32 s96, 5
	s_cselect_b64 s[16:17], -1, 0
	s_and_b64 s[0:1], s[16:17], s[0:1]
	v_mov_b32_e32 v1, v0
	s_andn2_b64 vcc, exec, s[0:1]
	s_cbranch_vccnz .LBB0_655
	s_lshl_b32 s0, s88, 3
	v_readlane_b32 s1, v254, 6
	s_add_i32 s4, s0, s1
	s_cmpk_gt_i32 s4, 0x40ff
	s_waitcnt vmcnt(0)
	v_and_b32_e32 v20, 63, v1
	s_cbranch_scc1 .LBB0_645
	v_lshlrev_b32_e32 v6, 6, v20
	v_mov_b32_e32 v7, 0
	v_mbcnt_lo_u32_b32 v2, -1, 0
	s_lshl_b32 s6, s68, 3
	v_lshl_add_u64 v[8:9], s[56:57], 0, v[6:7]
	v_lshlrev_b32_e32 v6, 5, v20
	v_mbcnt_hi_u32_b32 v14, -1, v2
	s_waitcnt lgkmcnt(3)
	v_lshl_add_u64 v[10:11], s[50:51], 0, v[6:7]
	s_mov_b64 s[0:1], 0x49c10000
	s_ashr_i32 s5, s4, 31
	s_ashr_i32 s7, s6, 31
	v_and_b32_e32 v2, 64, v14
	s_waitcnt lgkmcnt(0)
	v_lshl_add_u64 v[12:13], v[10:11], 0, s[0:1]
	s_lshl_b64 s[8:9], s[4:5], 11
	s_lshl_b64 s[10:11], s[6:7], 11
	s_mov_b32 s13, 0
	s_mov_b64 s[14:15], 0x46710000
	v_mov_b32_e32 v23, 0x358637bd
	s_mov_b32 s3, 0xf800000
	v_mov_b32_e32 v24, 0x260
	s_mov_b32 s20, 0x49c10000
	v_mov_b32_e32 v26, v7
	v_mov_b32_e32 v27, v7
	v_mov_b32_e32 v28, v7
	v_mov_b32_e32 v29, v7
	v_add_u32_e32 v15, 64, v2
	v_xor_b32_e32 v16, 1, v14
	v_xor_b32_e32 v17, 2, v14
	v_xor_b32_e32 v18, 4, v14
	v_xor_b32_e32 v19, 8, v14
	v_xor_b32_e32 v21, 16, v14
	v_xor_b32_e32 v22, 32, v14
	s_mov_b32 s12, s4
	global_load_dwordx4 v[110:113], v[8:9], off
	global_load_dwordx4 v[114:117], v[8:9], off offset:16
	global_load_dwordx4 v[118:121], v[8:9], off offset:32
	global_load_dwordx4 v[122:125], v[8:9], off offset:48
	s_cmpk_lt_i32 s12, 0x4010
	s_cbranch_scc0 .Lmy_ln_nopf0
	v_lshl_add_u64 v[108:109], v[10:11], 0, s[8:9]
	v_lshl_add_u64 v[108:109], v[108:109], 0, s[14:15]
	global_load_dwordx4 v[100:103], v[108:109], off offset:16
	global_load_dwordx4 v[104:107], v[108:109], off
.Lmy_ln_nopf0:
	s_waitcnt vmcnt(0)
	s_branch .LBB0_635

; __device__ __forceinline__ float bflo(unsigned w) { return __uint_as_float(w << 16); }
; __device__ __forceinline__ float bfhi(unsigned w) { return __uint_as_float(w & 0xffff0000u); }
; template <int N>
; __device__ __forceinline__ void lat_norm(const Frame& F, const bf16* src, const float* w, bf16* dst, int nvalid, int ntotal) {
;     ...
;         if (r < nvalid) {
; #pragma unroll
;             for (int j = 0; j < PER / 8; ++j) { const v4u t = *((const v4u*)(src + (size_t)r * N + F.lane * PER) + j); xw[4 * j] = t.x; xw[4 * j + 1] = t.y; xw[4 * j + 2] = t.z; xw[4 * j + 3] = t.w; }
; #pragma unroll
;             for (int j = 0; j < PER / 2; ++j) { x[2 * j] = bflo(xw[j]); x[2 * j + 1] = bfhi(xw[j]); s += x[2 * j] * x[2 * j] + x[2 * j + 1] * x[2 * j + 1]; }
;             const float rstd = 1.0f / sqrtf(wave_sum(s) * (1.0f / N) + EPS);
; #pragma unroll
;             for (int j = 0; j < PER / 8; ++j) { const f32x4 g0 = *(const f32x4*)(w + F.lane * PER + 8 * j), g1 = *(const f32x4*)(w + F.lane * PER + 8 * j + 4);
;                 v4u o; o.x = pk_bf16(x[8 * j] * rstd * g0.x, x[8 * j + 1] * rstd * g0.y); o.y = pk_bf16(x[8 * j + 2] * rstd * g0.z, x[8 * j + 3] * rstd * g0.w);
;                 o.z = pk_bf16(x[8 * j + 4] * rstd * g1.x, x[8 * j + 5] * rstd * g1.y); o.w = pk_bf16(x[8 * j + 6] * rstd * g1.z, x[8 * j + 7] * rstd * g1.w);
;                 *((v4u*)(dst + (size_t)r * N + F.lane * PER) + j) = o; }
.LBB0_637:
	v_mov_b32_e32 v2, 0
	s_andn2_b64 vcc, exec, s[18:19]
	v_mov_b32_e32 v3, 0
	v_mov_b32_e32 v4, 0
	v_mov_b32_e32 v5, 0
	s_cbranch_vccnz .LBB0_634
	v_lshl_add_u64 v[42:43], v[10:11], 0, s[8:9]
	s_waitcnt vmcnt(2)
	v_mov_b32_e32 v2, v100
	v_mov_b32_e32 v3, v101
	v_mov_b32_e32 v4, v102
	v_mov_b32_e32 v5, v103
	v_mov_b32_e32 v30, v104
	v_mov_b32_e32 v31, v105
	v_mov_b32_e32 v32, v106
	v_mov_b32_e32 v33, v107
	s_add_i32 s100, s12, s6
	s_cmpk_lt_i32 s100, 0x4010
	s_cbranch_scc0 .Lmy_ln_nopf
	s_add_u32 s98, s8, s10
	s_addc_u32 s99, s9, s11
	v_lshl_add_u64 v[108:109], v[10:11], 0, s[98:99]
	v_lshl_add_u64 v[108:109], v[108:109], 0, s[14:15]
	global_load_dwordx4 v[100:103], v[108:109], off offset:16
	global_load_dwordx4 v[104:107], v[108:109], off
.Lmy_ln_nopf:
	v_cmp_lt_i32_e32 vcc, v16, v15
	v_cndmask_b32_e32 v7, v14, v16, vcc
	v_lshlrev_b32_e32 v7, 2, v7
	v_cmp_lt_i32_e32 vcc, v17, v15
	v_lshlrev_b32_e32 v45, 16, v5
	v_lshlrev_b32_e32 v44, 16, v4
	v_and_b32_e32 v47, 0xffff0000, v5
	v_and_b32_e32 v46, 0xffff0000, v4
	v_lshlrev_b32_e32 v4, 16, v33
	v_and_b32_e32 v5, 0xffff0000, v33
	v_lshlrev_b32_e32 v48, 16, v32
	v_and_b32_e32 v49, 0xffff0000, v32
	v_lshlrev_b32_e32 v32, 16, v31
	v_and_b32_e32 v33, 0xffff0000, v31
	v_lshlrev_b32_e32 v50, 16, v30
	v_and_b32_e32 v51, 0xffff0000, v30
	v_pk_mul_f32 v[30:31], v[4:5], v[4:5]
	v_pk_mul_f32 v[58:59], v[32:33], v[32:33]
	v_pk_mul_f32 v[60:61], v[50:51], v[50:51]
	v_pk_mul_f32 v[56:57], v[48:49], v[48:49]
	v_add_f32_e32 v25, v30, v31
	v_add_f32_e32 v30, v58, v59
	v_add_f32_e32 v31, v60, v61
	v_lshlrev_b32_e32 v54, 16, v2
	v_and_b32_e32 v55, 0xffff0000, v2
	v_add_f32_e32 v56, v56, v57
	v_add_f32_e32 v30, v31, v30
	v_lshlrev_b32_e32 v52, 16, v3
	v_and_b32_e32 v53, 0xffff0000, v3
	v_pk_mul_f32 v[64:65], v[54:55], v[54:55]
	v_add_f32_e32 v30, v56, v30
	v_pk_mul_f32 v[62:63], v[52:53], v[52:53]
	v_add_f32_e32 v57, v64, v65
	v_add_f32_e32 v25, v25, v30
	v_pk_mul_f32 v[2:3], v[46:47], v[46:47]
	v_add_f32_e32 v58, v62, v63
	v_add_f32_e32 v25, v57, v25
	v_pk_fma_f32 v[2:3], v[44:45], v[44:45], v[2:3]
	v_add_f32_e32 v25, v58, v25
	v_add_f32_e32 v2, v2, v25
	v_add_f32_e32 v2, v3, v2
	ds_bpermute_b32 v3, v7, v2
	v_cndmask_b32_e32 v7, v14, v17, vcc
	v_lshlrev_b32_e32 v7, 2, v7
	v_cmp_lt_i32_e32 vcc, v18, v15
	s_waitcnt lgkmcnt(0)
	v_add_f32_e32 v2, v2, v3
	ds_bpermute_b32 v3, v7, v2
	v_cndmask_b32_e32 v7, v14, v18, vcc
	v_lshlrev_b32_e32 v7, 2, v7
	v_cmp_lt_i32_e32 vcc, v19, v15
	s_waitcnt lgkmcnt(0)
	v_add_f32_e32 v2, v2, v3
	ds_bpermute_b32 v3, v7, v2
	v_cndmask_b32_e32 v7, v14, v19, vcc
	v_lshlrev_b32_e32 v7, 2, v7
	v_cmp_lt_i32_e32 vcc, v21, v15
	s_waitcnt lgkmcnt(0)
	v_add_f32_e32 v2, v2, v3
	ds_bpermute_b32 v3, v7, v2
	v_cndmask_b32_e32 v7, v14, v21, vcc
	v_lshlrev_b32_e32 v7, 2, v7
	v_cmp_lt_i32_e32 vcc, v22, v15
	s_waitcnt lgkmcnt(0)
	v_add_f32_e32 v2, v2, v3
	ds_bpermute_b32 v3, v7, v2
	v_cndmask_b32_e32 v7, v14, v22, vcc
	v_lshlrev_b32_e32 v7, 2, v7
	s_waitcnt lgkmcnt(0)
	v_add_f32_e32 v2, v2, v3
	ds_bpermute_b32 v3, v7, v2
	s_waitcnt lgkmcnt(0)
	v_add_f32_e32 v2, v2, v3
	v_fmamk_f32 v2, v2, 0x3a800000, v23
	v_mul_f32_e32 v3, 0x4f800000, v2
	v_cmp_gt_f32_e32 vcc, s3, v2
	s_nop 1
	v_cndmask_b32_e32 v2, v2, v3, vcc
	v_sqrt_f32_e32 v3, v2
	s_nop 0
	v_add_u32_e32 v7, -1, v3
	v_add_u32_e32 v25, 1, v3
	v_fma_f32 v30, -v7, v3, v2
	v_fma_f32 v31, -v25, v3, v2
	v_cmp_ge_f32_e64 s[0:1], 0, v30
	s_nop 1
	v_cndmask_b32_e64 v3, v3, v7, s[0:1]
	v_cmp_lt_f32_e64 s[0:1], 0, v31
	s_nop 1
	v_cndmask_b32_e64 v3, v3, v25, s[0:1]
	v_mul_f32_e32 v7, 0x37800000, v3
	v_cndmask_b32_e32 v3, v3, v7, vcc
	v_cmp_class_f32_e32 vcc, v2, v24
	s_nop 1
	v_cndmask_b32_e32 v2, v3, v2, vcc
	v_div_scale_f32 v3, s[0:1], v2, v2, 1.0
	v_rcp_f32_e32 v7, v3
	v_add_co_u32_e32 v30, vcc, s20, v42
	s_mov_b64 s[0:1], s[8:9]
	s_nop 0
	v_addc_co_u32_e32 v31, vcc, 0, v43, vcc
	v_fma_f32 v42, -v3, v7, 1.0
	v_div_scale_f32 v25, vcc, 1.0, v2, 1.0
	v_fmac_f32_e32 v7, v42, v7
	v_mul_f32_e32 v42, v25, v7
	v_fma_f32 v43, -v3, v42, v25
	v_fmac_f32_e32 v42, v43, v7
	v_fma_f32 v3, -v3, v42, v25
	v_div_fmas_f32 v3, v3, v7, v42
	v_div_fixup_f32 v42, v3, v2, 1.0
	v_pk_mul_f32 v[2:3], v[42:43], v[50:51] op_sel_hi:[0,1]
	v_pk_mul_f32 v[32:33], v[42:43], v[32:33] op_sel_hi:[0,1]
	v_pk_mul_f32 v[48:49], v[42:43], v[48:49] op_sel_hi:[0,1]
	v_pk_mul_f32 v[4:5], v[42:43], v[4:5] op_sel_hi:[0,1]
	v_pk_mul_f32 v[2:3], v[110:111], v[2:3]
	v_pk_mul_f32 v[32:33], v[112:113], v[32:33]
	v_pk_mul_f32 v[34:35], v[114:115], v[48:49]
	v_pk_mul_f32 v[36:37], v[116:117], v[4:5]
	v_cvt_pk_bf16_f32 v2, v2, v3
	v_cvt_pk_bf16_f32 v3, v32, v33
	v_cvt_pk_bf16_f32 v4, v34, v35
	v_cvt_pk_bf16_f32 v5, v36, v37
	global_store_dwordx4 v[30:31], v[2:5], off
	v_mov_b32_e32 v34, v44
	v_mov_b32_e32 v35, v46
	v_mov_b32_e32 v46, v45
	v_pk_mul_f32 v[36:37], v[42:43], v[54:55] op_sel_hi:[0,1]
	v_pk_mul_f32 v[38:39], v[42:43], v[52:53] op_sel_hi:[0,1]
	v_pk_mul_f32 v[34:35], v[42:43], v[34:35] op_sel_hi:[0,1]
	v_pk_mul_f32 v[40:41], v[42:43], v[46:47] op_sel_hi:[0,1]
	v_pk_mul_f32 v[2:3], v[118:119], v[36:37]
	v_pk_mul_f32 v[4:5], v[120:121], v[38:39]
	v_pk_mul_f32 v[30:31], v[122:123], v[34:35]
	v_pk_mul_f32 v[32:33], v[124:125], v[40:41]
	v_cvt_pk_bf16_f32 v2, v2, v3
	v_cvt_pk_bf16_f32 v3, v4, v5
	v_cvt_pk_bf16_f32 v4, v30, v31
	v_cvt_pk_bf16_f32 v5, v32, v33
	s_branch .LBB0_634
